# grid-barrier spin loops: poll cadence s_sleep 1 -> s_sleep 0
# baseline (speedup 1.0000x reference)
.LBB0_14:
	s_sleep 0
	global_load_dword v2, v0, s[6:7] offset:32 sc1
	s_waitcnt vmcnt(0)
	v_and_b32_e32 v2, 0xffff0000, v2
	v_cmp_ne_u32_e32 vcc, v2, v1
	s_or_b64 s[8:9], vcc, s[8:9]
	s_andn2_b64 exec, exec, s[8:9]
	s_cbranch_execnz .LBB0_14

.LBB0_77:
	global_load_dword v16, v0, s[6:7] sc1
	s_waitcnt lgkmcnt(0)
	global_load_dword v1, v0, s[8:9] sc1
	global_load_dword v2, v0, s[20:21] sc1
	global_load_dword v3, v0, s[22:23] sc1
	global_load_dword v4, v0, s[24:25] sc1
	global_load_dword v5, v0, s[44:45] sc1
	global_load_dword v6, v0, s[46:47] sc1
	global_load_dword v7, v0, s[50:51] sc1
	global_load_dword v8, v0, s[52:53] sc1
	global_load_dword v9, v0, s[54:55] sc1
	global_load_dword v10, v0, s[56:57] sc1
	global_load_dword v11, v0, s[58:59] sc1
	global_load_dword v12, v0, s[60:61] sc1
	global_load_dword v13, v0, s[62:63] sc1
	global_load_dword v14, v0, s[64:65] sc1
	global_load_dword v15, v0, s[66:67] sc1
	s_mov_b64 s[68:69], -1
	s_mov_b64 s[70:71], -1
	s_waitcnt vmcnt(14)
	v_add_u32_e32 v17, v1, v16
	s_waitcnt vmcnt(13)
	v_add_u32_e32 v17, v17, v2
	s_waitcnt vmcnt(12)
	v_add_u32_e32 v17, v17, v3
	s_waitcnt vmcnt(11)
	v_add_u32_e32 v17, v17, v4
	s_waitcnt vmcnt(10)
	v_add_u32_e32 v17, v17, v5
	s_waitcnt vmcnt(9)
	v_add_u32_e32 v17, v17, v6
	s_waitcnt vmcnt(8)
	v_add_u32_e32 v17, v17, v7
	s_waitcnt vmcnt(7)
	v_add_u32_e32 v17, v17, v8
	s_waitcnt vmcnt(6)
	v_add_u32_e32 v17, v17, v9
	s_waitcnt vmcnt(5)
	v_add_u32_e32 v17, v17, v10
	s_waitcnt vmcnt(4)
	v_add_u32_e32 v17, v17, v11
	s_waitcnt vmcnt(3)
	v_add_u32_e32 v17, v17, v12
	s_waitcnt vmcnt(2)
	v_add_u32_e32 v17, v17, v13
	s_waitcnt vmcnt(1)
	v_add_u32_e32 v17, v17, v14
	s_waitcnt vmcnt(0)
	v_add_u32_e32 v17, v17, v15
	v_cmp_eq_u32_e32 vcc, s74, v17
	s_cbranch_vccnz .LBB0_76
	s_and_b32 s68, s75, 0xff
	s_cmp_eq_u32 s68, 0
	s_mov_b64 s[68:69], -1
	s_mov_b64 s[72:73], -1
	s_sleep 0
	s_cbranch_scc1 .LBB0_81
	s_and_b64 vcc, exec, s[72:73]
	s_cbranch_vccz .LBB0_76

.LBB0_95:
	s_and_b32 s50, s3, 0xff
	s_mov_b64 s[46:47], -1
	s_cmp_lg_u32 s50, 0
	s_mov_b64 s[52:53], -1
	s_sleep 0
	s_cbranch_scc0 .LBB0_98
	s_and_b64 vcc, exec, s[52:53]
	s_cbranch_vccz .LBB0_94

.LBB0_112:
	s_and_b32 s46, s3, 0xff
	s_cmp_lg_u32 s46, 0
	s_mov_b64 s[50:51], -1
	s_sleep 0
	s_cbranch_scc0 .LBB0_115
	s_mov_b64 s[52:53], -1
	s_and_b64 vcc, exec, s[50:51]
	s_cbranch_vccz .LBB0_111

.LBB0_289:
	global_load_dword v16, v0, s[6:7] sc1
	s_waitcnt lgkmcnt(0)
	global_load_dword v1, v0, s[8:9] sc1
	global_load_dword v2, v0, s[10:11] sc1
	global_load_dword v3, v0, s[12:13] sc1
	global_load_dword v4, v0, s[14:15] sc1
	global_load_dword v5, v0, s[16:17] sc1
	global_load_dword v6, v0, s[18:19] sc1
	global_load_dword v7, v0, s[20:21] sc1
	global_load_dword v8, v0, s[22:23] sc1
	global_load_dword v9, v0, s[24:25] sc1
	global_load_dword v10, v0, s[44:45] sc1
	global_load_dword v11, v0, s[46:47] sc1
	global_load_dword v12, v0, s[52:53] sc1
	global_load_dword v13, v0, s[54:55] sc1
	global_load_dword v14, v0, s[56:57] sc1
	global_load_dword v15, v0, s[58:59] sc1
	s_mov_b64 s[60:61], -1
	s_mov_b64 s[62:63], -1
	s_waitcnt vmcnt(14)
	v_add_u32_e32 v17, v1, v16
	s_waitcnt vmcnt(13)
	v_add_u32_e32 v17, v17, v2
	s_waitcnt vmcnt(12)
	v_add_u32_e32 v17, v17, v3
	s_waitcnt vmcnt(11)
	v_add_u32_e32 v17, v17, v4
	s_waitcnt vmcnt(10)
	v_add_u32_e32 v17, v17, v5
	s_waitcnt vmcnt(9)
	v_add_u32_e32 v17, v17, v6
	s_waitcnt vmcnt(8)
	v_add_u32_e32 v17, v17, v7
	s_waitcnt vmcnt(7)
	v_add_u32_e32 v17, v17, v8
	s_waitcnt vmcnt(6)
	v_add_u32_e32 v17, v17, v9
	s_waitcnt vmcnt(5)
	v_add_u32_e32 v17, v17, v10
	s_waitcnt vmcnt(4)
	v_add_u32_e32 v17, v17, v11
	s_waitcnt vmcnt(3)
	v_add_u32_e32 v17, v17, v12
	s_waitcnt vmcnt(2)
	v_add_u32_e32 v17, v17, v13
	s_waitcnt vmcnt(1)
	v_add_u32_e32 v17, v17, v14
	s_waitcnt vmcnt(0)
	v_add_u32_e32 v17, v17, v15
	v_cmp_eq_u32_e32 vcc, s50, v17
	s_cbranch_vccnz .LBB0_288
	s_and_b32 s60, s51, 0xff
	s_cmp_eq_u32 s60, 0
	s_mov_b64 s[60:61], -1
	s_mov_b64 s[64:65], -1
	s_sleep 0
	s_cbranch_scc1 .LBB0_293
	s_and_b64 vcc, exec, s[64:65]
	s_cbranch_vccz .LBB0_288

.LBB0_307:
	s_and_b32 s20, s3, 0xff
	s_mov_b64 s[18:19], -1
	s_cmp_lg_u32 s20, 0
	s_mov_b64 s[22:23], -1
	s_sleep 0
	s_cbranch_scc0 .LBB0_310
	s_and_b64 vcc, exec, s[22:23]
	s_cbranch_vccz .LBB0_306

.LBB0_324:
	s_and_b32 s18, s3, 0xff
	s_cmp_lg_u32 s18, 0
	s_mov_b64 s[20:21], -1
	s_sleep 0
	s_cbranch_scc0 .LBB0_327
	s_mov_b64 s[22:23], -1
	s_and_b64 vcc, exec, s[20:21]
	s_cbranch_vccz .LBB0_323

.LBB0_367:
	v_readlane_b32 s4, v253, 36
	v_readlane_b32 s5, v253, 37
	v_readlane_b32 s6, v255, 19
	s_waitcnt lgkmcnt(0)
	s_nop 2
	global_load_dword v0, v4, s[4:5] sc1
	v_readlane_b32 s4, v253, 38
	v_readlane_b32 s5, v253, 39
	s_nop 4
	global_load_dword v1, v4, s[4:5] sc1
	v_readlane_b32 s4, v253, 40
	v_readlane_b32 s5, v253, 41
	s_waitcnt vmcnt(0)
	v_add_u32_e32 v17, v1, v0
	s_nop 2
	global_load_dword v2, v4, s[4:5] sc1
	v_readlane_b32 s4, v253, 42
	v_readlane_b32 s5, v253, 43
	s_waitcnt vmcnt(0)
	v_add_u32_e32 v17, v17, v2
	s_nop 2
	global_load_dword v3, v4, s[4:5] sc1
	v_readlane_b32 s4, v253, 44
	v_readlane_b32 s5, v253, 45
	s_waitcnt vmcnt(0)
	v_add_u32_e32 v17, v17, v3
	s_nop 2
	global_load_dword v5, v4, s[4:5] sc1
	v_readlane_b32 s4, v253, 46
	v_readlane_b32 s5, v253, 47
	s_waitcnt vmcnt(0)
	v_add_u32_e32 v17, v17, v5
	s_nop 2
	global_load_dword v6, v4, s[4:5] sc1
	v_readlane_b32 s4, v253, 48
	v_readlane_b32 s5, v253, 49
	s_waitcnt vmcnt(0)
	v_add_u32_e32 v17, v17, v6
	s_nop 2
	global_load_dword v7, v4, s[4:5] sc1
	v_readlane_b32 s4, v253, 50
	v_readlane_b32 s5, v253, 51
	s_waitcnt vmcnt(0)
	v_add_u32_e32 v17, v17, v7
	s_nop 2
	global_load_dword v8, v4, s[4:5] sc1
	v_readlane_b32 s4, v253, 52
	v_readlane_b32 s5, v253, 53
	s_waitcnt vmcnt(0)
	v_add_u32_e32 v17, v17, v8
	s_nop 2
	global_load_dword v9, v4, s[4:5] sc1
	v_readlane_b32 s4, v253, 54
	v_readlane_b32 s5, v253, 55
	s_waitcnt vmcnt(0)
	v_add_u32_e32 v17, v17, v9
	s_nop 2
	global_load_dword v10, v4, s[4:5] sc1
	v_readlane_b32 s4, v253, 56
	v_readlane_b32 s5, v253, 57
	s_waitcnt vmcnt(0)
	v_add_u32_e32 v17, v17, v10
	s_nop 2
	global_load_dword v11, v4, s[4:5] sc1
	v_readlane_b32 s4, v253, 58
	v_readlane_b32 s5, v253, 59
	s_waitcnt vmcnt(0)
	v_add_u32_e32 v17, v17, v11
	s_nop 2
	global_load_dword v12, v4, s[4:5] sc1
	v_readlane_b32 s4, v253, 60
	v_readlane_b32 s5, v253, 61
	s_waitcnt vmcnt(0)
	v_add_u32_e32 v17, v17, v12
	s_nop 2
	global_load_dword v13, v4, s[4:5] sc1
	v_readlane_b32 s4, v253, 62
	v_readlane_b32 s5, v253, 63
	s_waitcnt vmcnt(0)
	v_add_u32_e32 v17, v17, v13
	s_nop 2
	global_load_dword v14, v4, s[4:5] sc1
	v_readlane_b32 s4, v254, 0
	v_readlane_b32 s5, v254, 1
	s_waitcnt vmcnt(0)
	v_add_u32_e32 v17, v17, v14
	s_nop 2
	global_load_dword v15, v4, s[4:5] sc1
	v_readlane_b32 s4, v254, 2
	v_readlane_b32 s5, v254, 3
	s_waitcnt vmcnt(0)
	v_add_u32_e32 v17, v17, v15
	s_nop 2
	global_load_dword v16, v4, s[4:5] sc1
	s_mov_b64 s[4:5], -1
	s_waitcnt vmcnt(0)
	v_add_u32_e32 v17, v17, v16
	v_cmp_eq_u32_e32 vcc, s6, v17
	s_mov_b64 s[6:7], -1
	s_cbranch_vccnz .LBB0_366
	s_and_b32 s4, s11, 0xff
	s_cmp_eq_u32 s4, 0
	s_mov_b64 s[4:5], -1
	s_mov_b64 s[8:9], -1
	s_sleep 0
	s_cbranch_scc1 .LBB0_371
	s_and_b64 vcc, exec, s[8:9]
	s_cbranch_vccz .LBB0_366

.LBB0_385:
	s_and_b32 s17, s16, 0xff
	s_mov_b64 s[20:21], -1
	s_cmp_lg_u32 s17, 0
	s_mov_b64 s[70:71], -1
	s_sleep 0
	s_cbranch_scc0 .LBB0_388
	s_and_b64 vcc, exec, s[70:71]
	s_cbranch_vccz .LBB0_384

.LBB0_402:
	s_and_b32 s17, s16, 0xff
	s_mov_b64 s[14:15], -1
	s_cmp_lg_u32 s17, 0
	s_mov_b64 s[22:23], -1
	s_sleep 0
	s_cbranch_scc0 .LBB0_405
	s_and_b64 vcc, exec, s[22:23]
	s_cbranch_vccz .LBB0_401

.LBB0_1633:
	s_and_b32 s18, s22, 0xff
	s_mov_b64 s[16:17], -1
	s_cmp_lg_u32 s18, 0
	s_mov_b64 s[20:21], -1
	s_sleep 0
	s_cbranch_scc0 .LBB0_1636
	s_and_b64 vcc, exec, s[20:21]
	s_cbranch_vccz .LBB0_1632

.LBB0_1650:
	s_and_b32 s16, s20, 0xff
	s_mov_b64 s[14:15], -1
	s_cmp_lg_u32 s16, 0
	s_mov_b64 s[18:19], -1
	s_sleep 0
	s_cbranch_scc0 .LBB0_1653
	s_and_b64 vcc, exec, s[18:19]
	s_cbranch_vccz .LBB0_1649
